# MLA tile loop: K-fragment LDS reads hoisted ahead of the QK MFMAs (counted lgkmcnt), V transpose reads issued during softmax
# speedup vs baseline: 1.0094x; 1.0094x over previous
; #define LAS __attribute__((address_space(3)))
; DI float shx(float v, int lane, int m) { return __builtin_bit_cast(float, __builtin_amdgcn_ds_bpermute((lane ^ m) << 2, __builtin_bit_cast(int, v))); }
; #define MFMA32(a, b, c) __builtin_amdgcn_mfma_f32_32x32x16_bf16((a), (b), (c), 0, 0, 0)
; DI void mla_item(int g_wave, LAS unsigned char* lds, const bf16_t* QN, const bf16_t* QR, const bf16_t* KN, const bf16_t* KRb, const bf16_t* VM, bf16_t* MIX,
;                  int kvbase, int qrow0, int nq, int head, int ntiles, int wt) {
;     ...
;         if (T < wt) {
;             LAS const unsigned char* base = lds + (T & 1) * BUF;
;             f32x16 s0, s1;
; #pragma unroll
;             for (int i = 0; i < 16; ++i) { s0[i] = 0.f; s1[i] = 0.f; }
; #pragma unroll
;             for (int s = 0; s < 6; ++s) {
;                 const bf16x8 a0 = *(LAS const bf16x8*)(base + r * KST + (16 * s + 8 * h) * 2);
;                 const bf16x8 a1 = *(LAS const bf16x8*)(base + (32 + r) * KST + (16 * s + 8 * h) * 2);
;                 s0 = MFMA32(a0, qf[s], s0); s1 = MFMA32(a1, qf[s], s1);
;             }
;             float mx = s0[0];
; #pragma unroll
;             for (int i = 0; i < 16; ++i) { mx = fmaxf(mx, s0[i]); mx = fmaxf(mx, s1[i]); }
;             mx = fmaxf(mx, shx(mx, lane, 32));
.LBB0_1012:
	s_or_b64 exec, exec, s[4:5]
	v_cmp_lt_i32_e32 vcc, s7, v118
	s_and_saveexec_b64 s[4:5], vcc
	s_cbranch_execz .LBB0_1014
	s_bitcmp1_b32 s7, 0
	s_cselect_b32 s8, 0x5800, 0
	s_add_i32 s8, s8, 0
	v_add3_u32 v109, s8, v122, v100
	ds_read_b128 v[150:153], v109
	ds_read_b128 v[154:157], v109 offset:6656
	ds_read_b128 v[158:161], v109 offset:32
	ds_read_b128 v[162:165], v109 offset:6688
	ds_read_b128 v[166:169], v109 offset:64
	ds_read_b128 v[170:173], v109 offset:6720
	ds_read_b128 v[174:177], v109 offset:96
	ds_read_b128 v[178:181], v109 offset:6752
	ds_read_b128 v[182:185], v109 offset:128
	ds_read_b128 v[186:189], v109 offset:6784
	ds_read_b128 v[190:193], v109 offset:160
	ds_read_b128 v[194:197], v109 offset:6816
	v_add3_u32 v198, s8, v116, v117
	s_waitcnt lgkmcnt(11)
	v_mfma_f32_32x32x16_bf16 v[48:63], v[150:153], v[84:87], 0
	s_waitcnt lgkmcnt(10)
	v_mfma_f32_32x32x16_bf16 v[32:47], v[154:157], v[84:87], 0
	s_waitcnt lgkmcnt(9)
	v_mfma_f32_32x32x16_bf16 v[48:63], v[158:161], v[80:83], v[48:63]
	s_waitcnt lgkmcnt(8)
	v_mfma_f32_32x32x16_bf16 v[32:47], v[162:165], v[80:83], v[32:47]
	s_waitcnt lgkmcnt(7)
	v_mfma_f32_32x32x16_bf16 v[48:63], v[166:169], v[76:79], v[48:63]
	s_waitcnt lgkmcnt(6)
	v_mfma_f32_32x32x16_bf16 v[32:47], v[170:173], v[76:79], v[32:47]
	s_waitcnt lgkmcnt(5)
	v_mfma_f32_32x32x16_bf16 v[48:63], v[174:177], v[68:71], v[48:63]
	s_waitcnt lgkmcnt(4)
	v_mfma_f32_32x32x16_bf16 v[32:47], v[178:181], v[68:71], v[32:47]
	s_waitcnt lgkmcnt(3)
	v_mfma_f32_32x32x16_bf16 v[48:63], v[182:185], v[72:75], v[48:63]
	s_waitcnt lgkmcnt(2)
	v_mfma_f32_32x32x16_bf16 v[32:47], v[186:189], v[72:75], v[32:47]
	s_waitcnt lgkmcnt(1)
	v_mfma_f32_32x32x16_bf16 v[48:63], v[190:193], v[64:67], v[48:63]
	s_waitcnt lgkmcnt(0)
	v_mfma_f32_32x32x16_bf16 v[32:47], v[194:197], v[64:67], v[32:47]
	ds_read_b64_tr_b16 v[200:201], v198 offset:13312
	ds_read_b64_tr_b16 v[202:203], v198 offset:14464
	ds_read_b64_tr_b16 v[204:205], v198 offset:13376
	ds_read_b64_tr_b16 v[206:207], v198 offset:14528
	ds_read_b64_tr_b16 v[208:209], v198 offset:15616
	ds_read_b64_tr_b16 v[210:211], v198 offset:16768
	ds_read_b64_tr_b16 v[212:213], v198 offset:15680
	ds_read_b64_tr_b16 v[214:215], v198 offset:16832
	s_nop 9
	v_max_f32_e32 v110, v48, v48
	s_nop 0
	v_max_f32_e32 v109, v32, v32
	v_max_f32_e32 v109, v110, v109
	v_max3_f32 v109, v109, v49, v33
	v_max3_f32 v109, v109, v50, v34
	v_max3_f32 v109, v109, v51, v35
	v_max3_f32 v109, v109, v52, v36
	v_max3_f32 v109, v109, v53, v37
	v_max3_f32 v109, v109, v54, v38
	v_max3_f32 v109, v109, v55, v39
	v_max3_f32 v109, v109, v56, v40
	v_max3_f32 v109, v109, v57, v41
	v_max3_f32 v109, v109, v58, v42
	v_max3_f32 v109, v109, v59, v43
	v_max3_f32 v109, v109, v60, v44
	v_max3_f32 v109, v109, v61, v45
	v_max3_f32 v109, v109, v62, v46
	v_max3_f32 v109, v109, v63, v47
	ds_bpermute_b32 v110, v103, v109
	s_waitcnt lgkmcnt(0)
; #define LAS __attribute__((address_space(3)))
; DI float ex2(float x) { return __builtin_amdgcn_exp2f(x); }
; #define MFMA32(a, b, c) __builtin_amdgcn_mfma_f32_32x32x16_bf16((a), (b), (c), 0, 0, 0)
; DI bf16x8 tr_frag(LAS const unsigned char* p, int hi_off) { s16x4 lo = trr(p), hi = trr(p + hi_off); return __builtin_shufflevector(lo, hi, 0, 1, 2, 3, 4, 5, 6, 7); }
; DI void mla_item(int g_wave, LAS unsigned char* lds, const bf16_t* QN, const bf16_t* QR, const bf16_t* KN, const bf16_t* KRb, const bf16_t* VM, bf16_t* MIX,
;                  int kvbase, int qrow0, int nq, int head, int ntiles, int wt) {
;     ...
;             const float m_new = fmaxf(m_run, mx), alpha = ex2(m_run - m_new);
;             m_run = m_new;
;             float ls = 0.f;
; #pragma unroll
;             for (int i = 0; i < 16; ++i) { s0[i] = ex2(s0[i] - m_new); s1[i] = ex2(s1[i] - m_new); ls += s0[i] + s1[i]; }
;             l_run = l_run * alpha + ls;
; #pragma unroll
;             for (int i = 0; i < 16; ++i) { o0[i] *= alpha; o1[i] *= alpha; }
;             LAS const unsigned char* vb = base + KB;
; #pragma unroll
;             for (int kt = 0; kt < 2; ++kt)
; #pragma unroll
;                 for (int ss = 0; ss < 2; ++ss) {
;                     const bf16x8 pb = packfrag(kt == 0 ? s0 : s1, ss);
;                     LAS const unsigned char* vp = vb + (32 * kt + 16 * ss + 4 * h + tq) * VST + (16 * blk + 4 * tp) * 2;
;                     const bf16x8 a0 = tr_frag(vp, 8 * VST), a1 = tr_frag(vp + 64, 8 * VST);
;                     o0 = MFMA32(a0, pb, o0); o1 = MFMA32(a1, pb, o1);
;                 }
	ds_read_b64_tr_b16 v[216:217], v198 offset:17920
	ds_read_b64_tr_b16 v[218:219], v198 offset:19072
	ds_read_b64_tr_b16 v[220:221], v198 offset:17984
	ds_read_b64_tr_b16 v[222:223], v198 offset:19136
	ds_read_b64_tr_b16 v[228:229], v198 offset:20224
	ds_read_b64_tr_b16 v[230:231], v198 offset:21376
	ds_read_b64_tr_b16 v[232:233], v198 offset:20288
	ds_read_b64_tr_b16 v[234:235], v198 offset:21440
	v_max3_f32 v124, v108, v109, v110
	v_sub_f32_e32 v32, v32, v124
	v_exp_f32_e32 v125, v32
	v_sub_f32_e32 v32, v49, v124
	v_sub_f32_e32 v132, v108, v124
	v_exp_f32_e32 v108, v32
	v_sub_f32_e32 v32, v33, v124
	v_sub_f32_e32 v33, v50, v124
	v_exp_f32_e32 v134, v33
	v_sub_f32_e32 v33, v34, v124
	v_exp_f32_e32 v126, v33
	v_sub_f32_e32 v33, v51, v124
	v_sub_f32_e32 v48, v48, v124
	v_exp_f32_e32 v110, v33
	v_sub_f32_e32 v33, v35, v124
	v_exp_f32_e32 v133, v48
	v_exp_f32_e32 v48, v33
	v_sub_f32_e32 v33, v52, v124
	v_exp_f32_e32 v135, v33
	v_sub_f32_e32 v33, v36, v124
	v_exp_f32_e32 v127, v33
	v_sub_f32_e32 v33, v53, v124
	v_exp_f32_e32 v112, v33
	v_sub_f32_e32 v33, v37, v124
	v_exp_f32_e32 v50, v33
	v_sub_f32_e32 v33, v54, v124
	v_exp_f32_e32 v136, v33
	v_sub_f32_e32 v33, v38, v124
	v_exp_f32_e32 v129, v33
	v_sub_f32_e32 v33, v55, v124
	v_exp_f32_e32 v130, v33
	v_sub_f32_e32 v33, v39, v124
	v_exp_f32_e32 v52, v33
	v_sub_f32_e32 v33, v56, v124
	v_exp_f32_e32 v138, v33
	v_sub_f32_e32 v33, v40, v124
	v_exp_f32_e32 v35, v33
	v_sub_f32_e32 v33, v57, v124
	v_exp_f32_e32 v54, v33
	v_sub_f32_e32 v33, v41, v124
	v_exp_f32_e32 v36, v33
	v_sub_f32_e32 v33, v58, v124
	v_exp_f32_e32 v139, v33
	v_sub_f32_e32 v33, v42, v124
	v_exp_f32_e32 v128, v33
	v_sub_f32_e32 v33, v59, v124
	v_exp_f32_e32 v56, v33
	v_sub_f32_e32 v33, v43, v124
	v_exp_f32_e32 v38, v33
	v_sub_f32_e32 v33, v60, v124
	v_exp_f32_e32 v140, v33
	v_sub_f32_e32 v33, v44, v124
	v_exp_f32_e32 v60, v33
	v_sub_f32_e32 v33, v61, v124
	v_exp_f32_e32 v58, v33
	v_sub_f32_e32 v33, v45, v124
	v_exp_f32_e32 v40, v33
	v_sub_f32_e32 v33, v62, v124
	v_exp_f32_e32 v32, v32
	v_exp_f32_e32 v61, v33
	v_sub_f32_e32 v33, v46, v124
	v_exp_f32_e32 v46, v33
	v_sub_f32_e32 v33, v63, v124
	v_exp_f32_e32 v44, v33
	v_sub_f32_e32 v33, v47, v124
	v_add_f32_e32 v109, v133, v125
	v_exp_f32_e32 v42, v33
	v_mov_b32_e32 v33, v225
	v_pk_add_f32 v[62:63], v[108:109], v[32:33]
	v_add_f32_e32 v111, v134, v126
	v_pk_add_f32 v[62:63], v[62:63], v[62:63] op_sel_hi:[0,1]
	v_mov_b32_e32 v49, v63
	v_pk_add_f32 v[62:63], v[110:111], v[48:49]
	v_add_f32_e32 v113, v135, v127
	v_pk_add_f32 v[62:63], v[62:63], v[62:63] op_sel_hi:[0,1]
	v_mov_b32_e32 v51, v63
	v_pk_add_f32 v[62:63], v[112:113], v[50:51]
	v_add_f32_e32 v131, v136, v129
	v_pk_add_f32 v[62:63], v[62:63], v[62:63] op_sel_hi:[0,1]
	v_mov_b32_e32 v53, v63
	v_exp_f32_e32 v34, v132
	v_pk_add_f32 v[62:63], v[130:131], v[52:53]
	v_cvt_pk_bf16_f32 v108, v133, v108
	v_cvt_pk_bf16_f32 v109, v134, v110
	v_cvt_pk_bf16_f32 v110, v135, v112
	v_cvt_pk_bf16_f32 v111, v136, v130
	v_pk_mul_f32 v[14:15], v[14:15], v[34:35] op_sel_hi:[1,0]
	v_pk_mul_f32 v[12:13], v[12:13], v[34:35] op_sel_hi:[1,0]
	v_pk_mul_f32 v[10:11], v[10:11], v[34:35] op_sel_hi:[1,0]
	v_pk_mul_f32 v[8:9], v[8:9], v[34:35] op_sel_hi:[1,0]
	v_pk_mul_f32 v[6:7], v[6:7], v[34:35] op_sel_hi:[1,0]
	v_pk_mul_f32 v[4:5], v[4:5], v[34:35] op_sel_hi:[1,0]
	v_pk_mul_f32 v[2:3], v[2:3], v[34:35] op_sel_hi:[1,0]
	v_pk_mul_f32 v[0:1], v[0:1], v[34:35] op_sel_hi:[1,0]
	v_pk_mul_f32 v[30:31], v[30:31], v[34:35] op_sel_hi:[1,0]
	v_pk_mul_f32 v[28:29], v[28:29], v[34:35] op_sel_hi:[1,0]
	v_pk_mul_f32 v[26:27], v[26:27], v[34:35] op_sel_hi:[1,0]
	v_pk_mul_f32 v[24:25], v[24:25], v[34:35] op_sel_hi:[1,0]
	v_pk_mul_f32 v[22:23], v[22:23], v[34:35] op_sel_hi:[1,0]
	v_pk_mul_f32 v[20:21], v[20:21], v[34:35] op_sel_hi:[1,0]
	v_pk_mul_f32 v[18:19], v[18:19], v[34:35] op_sel_hi:[1,0]
	v_pk_mul_f32 v[16:17], v[16:17], v[34:35] op_sel_hi:[1,0]
	s_waitcnt lgkmcnt(0)
	v_mfma_f32_32x32x16_bf16 v[0:15], v[200:203], v[108:111], v[0:15]
	v_pk_add_f32 v[62:63], v[62:63], v[62:63] op_sel_hi:[0,1]
	v_add_f32_e32 v55, v138, v35
	v_mov_b32_e32 v37, v63
	v_pk_add_f32 v[62:63], v[54:55], v[36:37]
	v_add_f32_e32 v57, v139, v128
	v_pk_add_f32 v[62:63], v[62:63], v[62:63] op_sel_hi:[0,1]
	v_mov_b32_e32 v39, v63
	s_waitcnt lgkmcnt(0)
	v_mfma_f32_32x32x16_bf16 v[16:31], v[204:207], v[108:111], v[16:31]
	v_add_f32_e64 v62, v56, v38
	v_add_f32_e64 v63, v57, v39
	v_cvt_pk_bf16_f32 v54, v138, v54
	v_cvt_pk_bf16_f32 v55, v139, v56
	v_cvt_pk_bf16_f32 v56, v140, v58
	v_cvt_pk_bf16_f32 v57, v61, v44
	v_pk_add_f32 v[62:63], v[62:63], v[62:63] op_sel_hi:[0,1]
	v_add_f32_e32 v59, v140, v60
	s_waitcnt lgkmcnt(2)
	v_mfma_f32_32x32x16_bf16 v[0:15], v[208:211], v[54:57], v[0:15]
	v_mov_b32_e32 v41, v63
	v_add_f32_e64 v62, v58, v40
	v_add_f32_e64 v63, v59, v41
	v_add_f32_e32 v45, v61, v46
	v_pk_add_f32 v[62:63], v[62:63], v[62:63] op_sel_hi:[0,1]
	v_mov_b32_e32 v43, v63
	v_pk_add_f32 v[62:63], v[44:45], v[42:43]
	v_cvt_pk_bf16_f32 v37, v128, v38
	s_waitcnt lgkmcnt(0)
	v_mfma_f32_32x32x16_bf16 v[16:31], v[212:215], v[54:57], v[16:31]
	v_cvt_pk_bf16_f32 v55, v126, v48
	v_cvt_pk_bf16_f32 v56, v127, v50
	v_cvt_pk_bf16_f32 v54, v125, v32
	v_cvt_pk_bf16_f32 v57, v129, v52
	v_cvt_pk_bf16_f32 v38, v60, v40
	v_cvt_pk_bf16_f32 v39, v46, v42
	s_waitcnt lgkmcnt(2)
	v_mfma_f32_32x32x16_bf16 v[0:15], v[216:219], v[54:57], v[0:15]
	v_cvt_pk_bf16_f32 v36, v35, v36
	v_add_f32_e32 v33, v62, v63
	v_fmac_f32_e32 v33, v115, v34
	v_mov_b32_e32 v115, v33
	s_waitcnt lgkmcnt(4)
	v_mfma_f32_32x32x16_bf16 v[16:31], v[220:223], v[54:57], v[16:31]
	v_mov_b32_e32 v108, v124
	s_waitcnt lgkmcnt(2)
	v_mfma_f32_32x32x16_bf16 v[0:15], v[228:231], v[36:39], v[0:15]
	s_waitcnt lgkmcnt(0)
	v_mfma_f32_32x32x16_bf16 v[16:31], v[232:235], v[36:39], v[16:31]
